# HGRN M-wave loop: three scalar f32 multiply pairs converted to v_pk_mul_f32 (bit-identical), on top of aligned loop heads
# speedup vs baseline: 1.0037x; 1.0037x over previous
; #define LAS __attribute__((address_space(3)))
; __device__ __forceinline__ unsigned pkbf(float lo, float hi) { const f32x2_m v = {lo, hi}; const bf16x2_m b = __builtin_convertvector(v, bf16x2_m); return __builtin_bit_cast(unsigned, b); }
; #define HG_MFMA(x, y, c) __builtin_amdgcn_mfma_f32_16x16x32_bf16((x), (y), (c), 0, 0, 0)
; #define HG_BAR() asm volatile("s_waitcnt lgkmcnt(0)\n\ts_barrier" ::: "memory")
; __device__ __forceinline__ void hgrn_unit(LAS unsigned char* lds, int b, int h, int vs, const bf16* QR, const _Float16* LF, const bf16* IO, bf16* OR_) {
;     ...
; #pragma unroll
;             for (int sj = 0; sj < 4; ++sj) { a[sj] = (f32x4){0.f, 0.f, 0.f, 0.f};
;                 if (sj <= mw) {
; #pragma unroll
;                     for (int kk = 0; kk < 4; ++kk) a[sj] = HG_MFMA(knf[sj][kk], qgf[kk], a[sj]);
;                     if (sj == mw) {
; #pragma unroll
;                         for (int r = 0; r < 4; ++r) if (4 * fq + r > fr) a[sj][r] = 0.f; }
;                 } }
; #pragma unroll
;             for (int vj = 0; vj < 2; ++vj) { o[vj] = (f32x4){0.f, 0.f, 0.f, 0.f};
; #pragma unroll
;                 for (int kk = 0; kk < 4; ++kk) o[vj] = HG_MFMA(stf[vj][kk], qgf[kk], o[vj]); }
; #pragma unroll
;             for (int ki = 0; ki < 2; ++ki)
; #pragma unroll
;                 for (int vj = 0; vj < 2; ++vj) { sacc[ki][vj] = sacc[ki][vj] * glv[ki]; sacc[ki][vj] = HG_MFMA(klf[ki][0], vtf[vj][0], sacc[ki][vj]); sacc[ki][vj] = HG_MFMA(klf[ki][1], vtf[vj][1], sacc[ki][vj]); }
; #pragma unroll
;             for (int sj = 0; sj < 4; ++sj) *(LAS v2u*)(lds + OFF_AM + ((16 * mw + fr) * TS + 16 * sj + 4 * fq) * 2) = (v2u){pkbf(a[sj][0], a[sj][1]), pkbf(a[sj][2], a[sj][3])};
;             HG_BAR();
;             bf16x8 amf[2];
; #pragma unroll
;             for (int ss = 0; ss < 2; ++ss) amf[ss] = HG_LD8(OFF_AM + ((16 * mw + fr) * TS + 32 * ss + 8 * fq) * 2);
; #pragma unroll
;             for (int ki = 0; ki < 2; ++ki)
; #pragma unroll
;                 for (int vj = 0; vj < 2; ++vj) *(LAS v2u*)(lds + OFF_ST + ((16 * vj + fr) * QS + 16 * (2 * mw + ki) + 4 * fq) * 2) = (v2u){pkbf(sacc[ki][vj][0], sacc[ki][vj][1]), pkbf(sacc[ki][vj][2], sacc[ki][vj][3])};
; #pragma unroll
;             for (int vj = 0; vj < 2; ++vj) {
; #pragma unroll
;                 for (int ss = 0; ss < 2; ++ss) if (32 * ss <= 16 * mw + 15) o[vj] = HG_MFMA(vtf[vj][ss], amf[ss], o[vj]);
.LBB0_1532:
	s_waitcnt lgkmcnt(14)
	v_mfma_f32_16x16x32_bf16 v[132:135], v[132:135], v[52:55], 0
	v_mov_b32_e32 v136, s43
	v_cndmask_b32_e64 v136, v148, v136, s[10:11]
	s_waitcnt lgkmcnt(5)
	v_pk_mul_f32 v[34:35], v[34:35], v[94:95]
	v_mfma_f32_16x16x32_bf16 v[52:55], v[116:119], v[52:55], 0
	v_pk_mul_f32 v[32:33], v[32:33], v[92:93]
	v_cndmask_b32_e64 v137, 0, v149, s[12:13]
	v_cndmask_b32_e64 v136, v136, v148, s[12:13]
	v_mfma_f32_16x16x32_bf16 v[112:115], v[112:115], v[56:59], v[132:135]
	v_cndmask_b32_e64 v138, v150, 0, s[14:15]
	v_cndmask_b32_e64 v139, v151, 0, s[16:17]
	v_pk_mul_f32 v[12:13], v[12:13], v[94:95]
	v_mfma_f32_16x16x32_bf16 v[52:55], v[120:123], v[56:59], v[52:55]
	v_pk_mul_f32 v[10:11], v[10:11], v[92:93]
	v_cndmask_b32_e64 v137, v149, v137, s[8:9]
	v_cndmask_b32_e64 v139, v151, v139, s[8:9]
	s_waitcnt lgkmcnt(4)
	v_mfma_f32_16x16x32_bf16 v[32:35], v[96:99], v[48:51], v[32:35]
	v_cndmask_b32_e64 v138, v150, v138, s[8:9]
	v_cndmask_b32_e64 v136, v148, v136, s[8:9]
	s_waitcnt lgkmcnt(2)
	v_pk_mul_f32 v[8:9], v[8:9], v[78:79]
	v_mfma_f32_16x16x32_bf16 v[10:13], v[96:99], v[40:43], v[10:13]
	v_pk_mul_f32 v[6:7], v[6:7], v[76:77]
	v_pk_mul_f32 v[4:5], v[4:5], v[78:79]
	v_pk_mul_f32 v[2:3], v[2:3], v[76:77]
	v_mfma_f32_16x16x32_bf16 v[104:107], v[104:107], v[60:63], v[112:115]
	v_cvt_pk_bf16_f32 v56, v136, v137
	v_cvt_pk_bf16_f32 v57, v138, v139
	v_cvt_pk_bf16_f32 v58, v72, v73
	v_mfma_f32_16x16x32_bf16 v[52:55], v[124:127], v[60:63], v[52:55]
	v_cvt_pk_bf16_f32 v59, v74, v75
	v_add_u32_e32 v60, 0xe000, v204
	ds_write2_b64 v60, v[56:57], v[58:59] offset0:64 offset1:68
	s_waitcnt lgkmcnt(2)
	v_mfma_f32_16x16x32_bf16 v[6:9], v[80:83], v[48:51], v[6:9]
	v_cvt_pk_bf16_f32 v56, v88, v89
	v_cvt_pk_bf16_f32 v57, v90, v91
	v_cvt_pk_bf16_f32 v58, v68, v69
	v_mfma_f32_16x16x32_bf16 v[2:5], v[80:83], v[40:43], v[2:5]
	v_cvt_pk_bf16_f32 v59, v70, v71
	ds_write2_b64 v60, v[56:57], v[58:59] offset0:72 offset1:76
	s_waitcnt lgkmcnt(0)
	s_barrier
	v_mfma_f32_16x16x32_bf16 v[32:35], v[100:103], v[44:47], v[32:35]
	ds_read_b128 v[60:63], v205 offset:57856
	ds_read_b128 v[56:59], v205 offset:57920
	s_add_i32 s18, 0, 0x10600
	s_andn2_b64 vcc, exec, s[24:25]
	v_mfma_f32_16x16x32_bf16 v[10:13], v[100:103], v[36:39], v[10:13]
	v_mfma_f32_16x16x32_bf16 v[104:107], v[108:111], v[64:67], v[104:107]
	s_waitcnt lgkmcnt(4)
	v_mfma_f32_16x16x32_bf16 v[6:9], v[84:87], v[44:47], v[6:9]
	v_mfma_f32_16x16x32_bf16 v[2:5], v[84:87], v[36:39], v[2:5]
	v_mfma_f32_16x16x32_bf16 v[52:55], v[128:131], v[64:67], v[52:55]
	v_cvt_pk_bf16_f32 v64, v32, v33
	v_cvt_pk_bf16_f32 v65, v34, v35
	v_add_u32_e32 v66, s18, v195
	ds_write_b64 v66, v[64:65]
	v_cvt_pk_bf16_f32 v64, v10, v11
	v_cvt_pk_bf16_f32 v65, v12, v13
	v_add_u32_e32 v66, s18, v196
	ds_write_b64 v66, v[64:65]
	v_cvt_pk_bf16_f32 v64, v6, v7
	v_cvt_pk_bf16_f32 v65, v8, v9
	v_add_u32_e32 v66, s18, v197
	s_waitcnt lgkmcnt(3)
	v_mfma_f32_16x16x32_bf16 v[48:51], v[48:51], v[60:63], v[104:107]
	ds_write_b64 v66, v[64:65]
	v_cvt_pk_bf16_f32 v64, v2, v3
	v_cvt_pk_bf16_f32 v65, v4, v5
	v_add_u32_e32 v66, s18, v198
	ds_write_b64 v66, v[64:65]
	v_cndmask_b32_e64 v64, 0, 1, s[24:25]
	v_cmp_ne_u32_e64 s[18:19], 1, v64
	s_cbranch_vccnz .LBB0_1534
	s_waitcnt lgkmcnt(4)
	v_mfma_f32_16x16x32_bf16 v[48:51], v[44:47], v[56:59], v[48:51]
